# seams after the gate/up GEMMs (2 and 10) also become 32-workgroup group barriers plus a wait on a counter that the weight-converting idle workgroups bump when their list is done
# speedup vs baseline: 1.0092x; 1.0051x over previous
.LBB0_264:
	s_lshl_b32 s15, s24, 8
	s_add_i32 s15, s15, s63
	s_lshl_b32 s17, s25, 7
	v_or_b32_e32 v155, s15, v150
	s_or_b32 s17, s17, s68
	s_ashr_i32 s15, s15, 8
	s_ashr_i32 s24, s17, 6
	s_mulk_i32 s15, 0x58
	s_ashr_i32 s25, s24, 31
	s_ashr_i32 s17, s15, 31
	s_add_u32 s26, s15, s24
	s_addc_u32 s27, s17, s25
	s_lshl_b64 s[26:27], s[26:27], 15
	s_add_u32 s26, s38, s26
	v_lshlrev_b32_e32 v138, 7, v155
	s_addc_u32 s27, s39, s27
	v_and_b32_e32 v138, 0x6780, v138
	v_lshl_add_u64 v[156:157], s[26:27], 0, v[138:139]
	v_mul_f32_e32 v138, 0xbfb8aa3b, v126
	v_exp_f32_e32 v138, v138
	v_mul_f32_e32 v149, 0xbfb8aa3b, v127
	v_exp_f32_e32 v158, v149
	v_mov_b32_e32 v149, v139
	v_add_f32_e32 v138, 1.0, v138
	v_rcp_f32_e32 v138, v138
	v_add_f32_e32 v158, 1.0, v158
	v_rcp_f32_e32 v158, v158
	v_lshl_add_u64 v[156:157], v[156:157], 0, v[148:149]
	v_mul_f32_e32 v126, v126, v138
	v_mul_f32_e32 v118, v126, v118
	v_mul_f32_e32 v126, v127, v158
	v_mul_f32_e32 v127, 0xbfb8aa3b, v128
	v_exp_f32_e32 v127, v127
	v_mul_f32_e32 v138, 0xbfb8aa3b, v129
	v_exp_f32_e32 v138, v138
	v_mul_f32_e32 v119, v126, v119
	v_add_f32_e32 v126, 1.0, v127
	v_rcp_f32_e32 v126, v126
	v_add_f32_e32 v127, 1.0, v138
	v_rcp_f32_e32 v127, v127
	v_cvt_pk_bf16_f32 v118, v118, v119
	v_mul_f32_e32 v119, v128, v126
	v_mul_f32_e32 v126, 0xbfb8aa3b, v122
	v_exp_f32_e32 v126, v126
	v_mul_f32_e32 v119, v119, v120
	v_mul_f32_e32 v120, v129, v127
	v_mul_f32_e32 v127, 0xbfb8aa3b, v123
	v_exp_f32_e32 v127, v127
	v_mul_f32_e32 v120, v120, v121
	v_add_f32_e32 v121, 1.0, v126
	v_rcp_f32_e32 v121, v121
	v_add_f32_e32 v126, 1.0, v127
	v_rcp_f32_e32 v126, v126
	v_cvt_pk_bf16_f32 v119, v119, v120
	v_mul_f32_e32 v120, v122, v121
	v_mul_f32_e32 v121, 0xbfb8aa3b, v124
	v_exp_f32_e32 v121, v121
	v_mul_f32_e32 v122, 0xbfb8aa3b, v125
	v_exp_f32_e32 v122, v122
	v_mul_f32_e32 v114, v120, v114
	v_mul_f32_e32 v120, v123, v126
	v_mul_f32_e32 v115, v120, v115
	v_add_f32_e32 v120, 1.0, v121
	v_rcp_f32_e32 v121, v120
	v_add_f32_e32 v120, 1.0, v122
	v_rcp_f32_e32 v122, v120
	v_cvt_pk_bf16_f32 v120, v114, v115
	v_mul_f32_e32 v114, v124, v121
	v_mul_f32_e32 v114, v114, v116
	v_mul_f32_e32 v115, v125, v122
	v_mul_f32_e32 v116, 0xbfb8aa3b, v110
	v_mul_f32_e32 v115, v115, v117
	v_exp_f32_e32 v116, v116
	v_mul_f32_e32 v117, 0xbfb8aa3b, v111
	v_exp_f32_e32 v117, v117
	v_cvt_pk_bf16_f32 v121, v114, v115
	v_add_f32_e32 v114, 1.0, v116
	v_rcp_f32_e32 v114, v114
	v_add_f32_e32 v115, 1.0, v117
	v_rcp_f32_e32 v115, v115
	global_store_dwordx4 v[156:157], v[118:121], off sc1
	v_mul_f32_e32 v110, v110, v114
	v_mul_f32_e32 v102, v110, v102
	v_mul_f32_e32 v110, v111, v115
	v_mul_f32_e32 v111, 0xbfb8aa3b, v112
	v_exp_f32_e32 v111, v111
	v_mul_f32_e32 v114, 0xbfb8aa3b, v113
	v_exp_f32_e32 v114, v114
	v_mul_f32_e32 v103, v110, v103
	v_add_f32_e32 v110, 1.0, v111
	v_rcp_f32_e32 v110, v110
	v_add_f32_e32 v111, 1.0, v114
	v_rcp_f32_e32 v111, v111
	v_cvt_pk_bf16_f32 v102, v102, v103
	v_mul_f32_e32 v103, v112, v110
	v_mul_f32_e32 v110, 0xbfb8aa3b, v106
	v_exp_f32_e32 v110, v110
	v_mul_f32_e32 v103, v103, v104
	v_mul_f32_e32 v104, v113, v111
	v_mul_f32_e32 v111, 0xbfb8aa3b, v107
	v_exp_f32_e32 v111, v111
	v_mul_f32_e32 v104, v104, v105
	v_add_f32_e32 v105, 1.0, v110
	v_rcp_f32_e32 v105, v105
	v_add_f32_e32 v110, 1.0, v111
	v_rcp_f32_e32 v110, v110
	v_cvt_pk_bf16_f32 v103, v103, v104
	v_mul_f32_e32 v104, v106, v105
	v_mul_f32_e32 v105, 0xbfb8aa3b, v108
	v_exp_f32_e32 v105, v105
	v_mul_f32_e32 v106, 0xbfb8aa3b, v109
	v_exp_f32_e32 v106, v106
	v_mul_f32_e32 v98, v104, v98
	v_mul_f32_e32 v104, v107, v110
	v_mul_f32_e32 v99, v104, v99
	v_add_f32_e32 v104, 1.0, v105
	v_rcp_f32_e32 v105, v104
	v_add_f32_e32 v104, 1.0, v106
	v_rcp_f32_e32 v106, v104
	v_cvt_pk_bf16_f32 v104, v98, v99
	v_mul_f32_e32 v98, v108, v105
	v_mul_f32_e32 v98, v98, v100
	v_mul_f32_e32 v99, v109, v106
	v_mul_f32_e32 v100, 0xbfb8aa3b, v94
	v_mul_f32_e32 v99, v99, v101
	v_exp_f32_e32 v100, v100
	v_mul_f32_e32 v101, 0xbfb8aa3b, v95
	v_exp_f32_e32 v101, v101
	v_cvt_pk_bf16_f32 v105, v98, v99
	v_add_f32_e32 v98, 1.0, v100
	v_rcp_f32_e32 v98, v98
	v_add_f32_e32 v99, 1.0, v101
	v_rcp_f32_e32 v99, v99
	global_store_dwordx4 v[156:157], v[102:105], off offset:2048 sc1
	v_mul_f32_e32 v94, v94, v98
	v_mul_f32_e32 v86, v94, v86
	v_mul_f32_e32 v94, v95, v99
	v_mul_f32_e32 v95, 0xbfb8aa3b, v96
	v_exp_f32_e32 v95, v95
	v_mul_f32_e32 v98, 0xbfb8aa3b, v97
	v_exp_f32_e32 v98, v98
	v_mul_f32_e32 v87, v94, v87
	v_add_f32_e32 v94, 1.0, v95
	v_rcp_f32_e32 v94, v94
	v_add_f32_e32 v95, 1.0, v98
	v_rcp_f32_e32 v95, v95
	v_cvt_pk_bf16_f32 v86, v86, v87
	v_mul_f32_e32 v87, v96, v94
	v_mul_f32_e32 v94, 0xbfb8aa3b, v90
	v_exp_f32_e32 v94, v94
	v_mul_f32_e32 v87, v87, v88
	v_mul_f32_e32 v88, v97, v95
	v_mul_f32_e32 v95, 0xbfb8aa3b, v91
	v_exp_f32_e32 v95, v95
	v_mul_f32_e32 v88, v88, v89
	v_add_f32_e32 v89, 1.0, v94
	v_rcp_f32_e32 v89, v89
	v_add_f32_e32 v94, 1.0, v95
	v_rcp_f32_e32 v94, v94
	v_cvt_pk_bf16_f32 v87, v87, v88
	v_mul_f32_e32 v88, v90, v89
	v_mul_f32_e32 v89, 0xbfb8aa3b, v92
	v_exp_f32_e32 v89, v89
	v_mul_f32_e32 v90, 0xbfb8aa3b, v93
	v_exp_f32_e32 v90, v90
	v_mul_f32_e32 v82, v88, v82
	v_mul_f32_e32 v88, v91, v94
	v_mul_f32_e32 v83, v88, v83
	v_add_f32_e32 v88, 1.0, v89
	v_rcp_f32_e32 v89, v88
	v_add_f32_e32 v88, 1.0, v90
	v_rcp_f32_e32 v90, v88
	v_cvt_pk_bf16_f32 v88, v82, v83
	v_mul_f32_e32 v82, v92, v89
	v_mul_f32_e32 v82, v82, v84
	v_mul_f32_e32 v83, v93, v90
	v_mul_f32_e32 v83, v83, v85
	v_cvt_pk_bf16_f32 v89, v82, v83
	v_mul_f32_e32 v82, 0xbfb8aa3b, v78
	v_exp_f32_e32 v84, v82
	v_mul_f32_e32 v82, 0xbfb8aa3b, v79
	v_exp_f32_e32 v85, v82
	v_add_co_u32_e32 v82, vcc, s75, v156
	v_add_f32_e32 v84, 1.0, v84
	v_rcp_f32_e32 v84, v84
	v_add_f32_e32 v85, 1.0, v85
	v_rcp_f32_e32 v85, v85
	v_addc_co_u32_e32 v83, vcc, 0, v157, vcc
	v_mul_f32_e32 v78, v78, v84
	v_mul_f32_e32 v70, v78, v70
	v_mul_f32_e32 v78, v79, v85
	v_mul_f32_e32 v79, 0xbfb8aa3b, v80
	v_exp_f32_e32 v79, v79
	v_mul_f32_e32 v84, 0xbfb8aa3b, v81
	v_exp_f32_e32 v84, v84
	v_mul_f32_e32 v71, v78, v71
	v_add_f32_e32 v78, 1.0, v79
	v_rcp_f32_e32 v78, v78
	v_add_f32_e32 v79, 1.0, v84
	global_store_dwordx4 v[82:83], v[86:89], off sc1
	v_rcp_f32_e32 v79, v79
	v_cvt_pk_bf16_f32 v70, v70, v71
	v_mul_f32_e32 v71, v80, v78
	v_mul_f32_e32 v78, 0xbfb8aa3b, v74
	v_exp_f32_e32 v78, v78
	v_mul_f32_e32 v71, v71, v72
	v_mul_f32_e32 v72, v81, v79
	v_mul_f32_e32 v79, 0xbfb8aa3b, v75
	v_exp_f32_e32 v79, v79
	v_mul_f32_e32 v72, v72, v73
	v_add_f32_e32 v73, 1.0, v78
	v_rcp_f32_e32 v73, v73
	v_add_f32_e32 v78, 1.0, v79
	v_rcp_f32_e32 v78, v78
	v_cvt_pk_bf16_f32 v71, v71, v72
	v_mul_f32_e32 v72, v74, v73
	v_mul_f32_e32 v73, 0xbfb8aa3b, v76
	v_exp_f32_e32 v73, v73
	v_mul_f32_e32 v74, 0xbfb8aa3b, v77
	v_exp_f32_e32 v74, v74
	v_mul_f32_e32 v66, v72, v66
	v_mul_f32_e32 v72, v75, v78
	v_mul_f32_e32 v67, v72, v67
	v_add_f32_e32 v72, 1.0, v73
	v_rcp_f32_e32 v73, v72
	v_add_f32_e32 v72, 1.0, v74
	v_rcp_f32_e32 v74, v72
	v_cvt_pk_bf16_f32 v72, v66, v67
	v_mul_f32_e32 v66, v76, v73
	v_mul_f32_e32 v66, v66, v68
	v_mul_f32_e32 v67, v77, v74
	v_add_u32_e32 v68, 0x80, v155
	v_mul_f32_e32 v67, v67, v69
	v_cvt_pk_bf16_f32 v73, v66, v67
	v_lshrrev_b32_e32 v66, 8, v68
	v_lshlrev_b32_e32 v68, 7, v68
	v_and_b32_e32 v138, 0x6780, v68
	v_mul_f32_e32 v68, 0xbfb8aa3b, v62
	v_exp_f32_e32 v68, v68
	v_mul_f32_e32 v69, 0xbfb8aa3b, v63
	v_exp_f32_e32 v69, v69
	global_store_dwordx4 v[82:83], v[70:73], off offset:2048 sc1
	v_add_f32_e32 v68, 1.0, v68
	v_rcp_f32_e32 v68, v68
	v_add_f32_e32 v69, 1.0, v69
	v_rcp_f32_e32 v69, v69
	v_mul_i32_i24_e32 v66, 0x58, v66
	v_mul_f32_e32 v62, v62, v68
	v_mul_f32_e32 v54, v62, v54
	v_mul_f32_e32 v62, v63, v69
	v_mul_f32_e32 v63, 0xbfb8aa3b, v64
	v_exp_f32_e32 v63, v63
	v_mul_f32_e32 v68, 0xbfb8aa3b, v65
	v_exp_f32_e32 v68, v68
	v_mul_f32_e32 v55, v62, v55
	v_add_f32_e32 v62, 1.0, v63
	v_rcp_f32_e32 v62, v62
	v_add_f32_e32 v63, 1.0, v68
	v_rcp_f32_e32 v63, v63
	v_cvt_pk_bf16_f32 v54, v54, v55
	v_mul_f32_e32 v55, v64, v62
	v_mul_f32_e32 v62, 0xbfb8aa3b, v58
	v_exp_f32_e32 v62, v62
	v_mul_f32_e32 v55, v55, v56
	v_mul_f32_e32 v56, v65, v63
	v_mul_f32_e32 v63, 0xbfb8aa3b, v59
	v_exp_f32_e32 v63, v63
	v_mul_f32_e32 v56, v56, v57
	v_add_f32_e32 v57, 1.0, v62
	v_rcp_f32_e32 v57, v57
	v_add_f32_e32 v62, 1.0, v63
	v_rcp_f32_e32 v62, v62
	v_cvt_pk_bf16_f32 v55, v55, v56
	v_mul_f32_e32 v56, v58, v57
	v_mul_f32_e32 v57, 0xbfb8aa3b, v60
	v_exp_f32_e32 v57, v57
	v_mul_f32_e32 v58, 0xbfb8aa3b, v61
	v_exp_f32_e32 v58, v58
	v_mul_f32_e32 v50, v56, v50
	v_mul_f32_e32 v56, v59, v62
	v_mul_f32_e32 v51, v56, v51
	v_add_f32_e32 v56, 1.0, v57
	v_rcp_f32_e32 v57, v56
	v_add_f32_e32 v56, 1.0, v58
	v_rcp_f32_e32 v58, v56
	v_cvt_pk_bf16_f32 v56, v50, v51
	v_mul_f32_e32 v50, v60, v57
	v_mul_f32_e32 v50, v50, v52
	v_mul_f32_e32 v51, v61, v58
	v_mul_f32_e32 v52, 0xbfb8aa3b, v46
	v_mul_f32_e32 v51, v51, v53
	v_exp_f32_e32 v52, v52
	v_mul_f32_e32 v53, 0xbfb8aa3b, v47
	v_exp_f32_e32 v53, v53
	v_cvt_pk_bf16_f32 v57, v50, v51
	v_add_f32_e32 v50, 1.0, v52
	v_rcp_f32_e32 v50, v50
	v_add_f32_e32 v51, 1.0, v53
	v_rcp_f32_e32 v51, v51
	v_ashrrev_i32_e32 v67, 31, v66
	v_mul_f32_e32 v46, v46, v50
	v_mul_f32_e32 v38, v46, v38
	v_mul_f32_e32 v46, v47, v51
	v_mul_f32_e32 v47, 0xbfb8aa3b, v48
	v_exp_f32_e32 v47, v47
	v_mul_f32_e32 v50, 0xbfb8aa3b, v49
	v_lshl_add_u64 v[66:67], v[66:67], 0, s[24:25]
	v_exp_f32_e32 v50, v50
	v_mul_f32_e32 v39, v46, v39
	v_add_f32_e32 v46, 1.0, v47
	v_lshlrev_b64 v[66:67], 15, v[66:67]
	v_rcp_f32_e32 v46, v46
	v_lshl_add_u64 v[66:67], s[38:39], 0, v[66:67]
	v_lshl_add_u64 v[66:67], v[66:67], 0, v[138:139]
	v_lshl_add_u64 v[66:67], v[66:67], 0, v[148:149]
	v_add_f32_e32 v47, 1.0, v50
	global_store_dwordx4 v[66:67], v[54:57], off sc1
	v_rcp_f32_e32 v47, v47
	v_cvt_pk_bf16_f32 v38, v38, v39
	v_mul_f32_e32 v39, v48, v46
	v_mul_f32_e32 v46, 0xbfb8aa3b, v42
	v_exp_f32_e32 v46, v46
	v_mul_f32_e32 v39, v39, v40
	v_mul_f32_e32 v40, v49, v47
	v_mul_f32_e32 v47, 0xbfb8aa3b, v43
	v_exp_f32_e32 v47, v47
	v_mul_f32_e32 v40, v40, v41
	v_add_f32_e32 v41, 1.0, v46
	v_rcp_f32_e32 v41, v41
	v_add_f32_e32 v46, 1.0, v47
	v_rcp_f32_e32 v46, v46
	v_cvt_pk_bf16_f32 v39, v39, v40
	v_mul_f32_e32 v40, v42, v41
	v_mul_f32_e32 v41, 0xbfb8aa3b, v44
	v_exp_f32_e32 v41, v41
	v_mul_f32_e32 v42, 0xbfb8aa3b, v45
	v_exp_f32_e32 v42, v42
	v_mul_f32_e32 v34, v40, v34
	v_mul_f32_e32 v40, v43, v46
	v_mul_f32_e32 v35, v40, v35
	v_add_f32_e32 v40, 1.0, v41
	v_rcp_f32_e32 v41, v40
	v_add_f32_e32 v40, 1.0, v42
	v_rcp_f32_e32 v42, v40
	v_cvt_pk_bf16_f32 v40, v34, v35
	v_mul_f32_e32 v34, v44, v41
	v_mul_f32_e32 v34, v34, v36
	v_mul_f32_e32 v35, v45, v42
	v_mul_f32_e32 v36, 0xbfb8aa3b, v30
	v_mul_f32_e32 v35, v35, v37
	v_exp_f32_e32 v36, v36
	v_mul_f32_e32 v37, 0xbfb8aa3b, v31
	v_exp_f32_e32 v37, v37
	v_cvt_pk_bf16_f32 v41, v34, v35
	v_add_f32_e32 v34, 1.0, v36
	v_rcp_f32_e32 v34, v34
	v_add_f32_e32 v35, 1.0, v37
	v_rcp_f32_e32 v35, v35
	global_store_dwordx4 v[66:67], v[38:41], off offset:2048 sc1
	v_mul_f32_e32 v30, v30, v34
	v_mul_f32_e32 v22, v30, v22
	v_mul_f32_e32 v30, v31, v35
	v_mul_f32_e32 v31, 0xbfb8aa3b, v32
	v_exp_f32_e32 v31, v31
	v_mul_f32_e32 v34, 0xbfb8aa3b, v33
	v_exp_f32_e32 v34, v34
	v_mul_f32_e32 v23, v30, v23
	v_add_f32_e32 v30, 1.0, v31
	v_rcp_f32_e32 v30, v30
	v_add_f32_e32 v31, 1.0, v34
	v_rcp_f32_e32 v31, v31
	v_cvt_pk_bf16_f32 v22, v22, v23
	v_mul_f32_e32 v23, v32, v30
	v_mul_f32_e32 v30, 0xbfb8aa3b, v26
	v_exp_f32_e32 v30, v30
	v_mul_f32_e32 v23, v23, v24
	v_mul_f32_e32 v24, v33, v31
	v_mul_f32_e32 v31, 0xbfb8aa3b, v27
	v_exp_f32_e32 v31, v31
	v_mul_f32_e32 v24, v24, v25
	v_add_f32_e32 v25, 1.0, v30
	v_rcp_f32_e32 v25, v25
	v_add_f32_e32 v30, 1.0, v31
	v_rcp_f32_e32 v30, v30
	v_cvt_pk_bf16_f32 v23, v23, v24
	v_mul_f32_e32 v24, v26, v25
	v_mul_f32_e32 v25, 0xbfb8aa3b, v28
	v_exp_f32_e32 v25, v25
	v_mul_f32_e32 v26, 0xbfb8aa3b, v29
	v_exp_f32_e32 v26, v26
	v_mul_f32_e32 v18, v24, v18
	v_mul_f32_e32 v24, v27, v30
	v_mul_f32_e32 v19, v24, v19
	v_add_f32_e32 v24, 1.0, v25
	v_rcp_f32_e32 v25, v24
	v_add_f32_e32 v24, 1.0, v26
	v_rcp_f32_e32 v26, v24
	v_cvt_pk_bf16_f32 v24, v18, v19
	v_mul_f32_e32 v18, v28, v25
	v_mul_f32_e32 v18, v18, v20
	v_mul_f32_e32 v19, v29, v26
	v_mul_f32_e32 v19, v19, v21
	v_cvt_pk_bf16_f32 v25, v18, v19
	v_mul_f32_e32 v18, 0xbfb8aa3b, v14
	v_exp_f32_e32 v20, v18
	v_mul_f32_e32 v18, 0xbfb8aa3b, v15
	v_exp_f32_e32 v21, v18
	v_add_co_u32_e32 v18, vcc, s75, v66
	v_add_f32_e32 v20, 1.0, v20
	v_rcp_f32_e32 v20, v20
	v_add_f32_e32 v21, 1.0, v21
	v_rcp_f32_e32 v21, v21
	v_addc_co_u32_e32 v19, vcc, 0, v67, vcc
	v_mul_f32_e32 v14, v14, v20
	v_mul_f32_e32 v6, v14, v6
	v_mul_f32_e32 v14, v15, v21
	v_mul_f32_e32 v15, 0xbfb8aa3b, v16
	v_exp_f32_e32 v15, v15
	v_mul_f32_e32 v20, 0xbfb8aa3b, v17
	v_exp_f32_e32 v20, v20
	v_mul_f32_e32 v7, v14, v7
	v_add_f32_e32 v14, 1.0, v15
	v_rcp_f32_e32 v14, v14
	v_add_f32_e32 v15, 1.0, v20
	global_store_dwordx4 v[18:19], v[22:25], off sc1
	v_rcp_f32_e32 v15, v15
	v_cvt_pk_bf16_f32 v6, v6, v7
	v_mul_f32_e32 v7, v16, v14
	v_mul_f32_e32 v14, 0xbfb8aa3b, v10
	v_exp_f32_e32 v14, v14
	v_mul_f32_e32 v7, v7, v8
	v_mul_f32_e32 v8, v17, v15
	v_mul_f32_e32 v15, 0xbfb8aa3b, v11
	v_exp_f32_e32 v15, v15
	v_mul_f32_e32 v8, v8, v9
	v_add_f32_e32 v9, 1.0, v14
	v_rcp_f32_e32 v9, v9
	v_add_f32_e32 v14, 1.0, v15
	v_rcp_f32_e32 v14, v14
	v_cvt_pk_bf16_f32 v7, v7, v8
	v_mul_f32_e32 v8, v10, v9
	v_mul_f32_e32 v9, 0xbfb8aa3b, v12
	v_exp_f32_e32 v9, v9
	v_mul_f32_e32 v10, 0xbfb8aa3b, v13
	v_exp_f32_e32 v10, v10
	v_mul_f32_e32 v2, v8, v2
	v_mul_f32_e32 v8, v11, v14
	v_mul_f32_e32 v3, v8, v3
	v_add_f32_e32 v8, 1.0, v9
	v_rcp_f32_e32 v9, v8
	v_add_f32_e32 v8, 1.0, v10
	v_rcp_f32_e32 v10, v8
	v_cvt_pk_bf16_f32 v8, v2, v3
	v_mul_f32_e32 v2, v12, v9
	s_andn2_b64 vcc, exec, s[0:1]
	v_mul_f32_e32 v3, v13, v10
	s_mov_b64 s[0:1], -1
	v_mul_f32_e32 v2, v2, v4
	v_mul_f32_e32 v3, v3, v5
	v_cvt_pk_bf16_f32 v9, v2, v3
	global_store_dwordx4 v[18:19], v[6:9], off offset:2048 sc1
	s_cbranch_vccnz .LBB0_257
	s_andn2_b64 vcc, exec, s[6:7]
	s_cbranch_vccnz .LBB0_256
	s_barrier
	s_branch .LBB0_256

.LBB0_272:
	v_cndmask_b32_e64 v34, v74, v75, s[18:19]
	v_add_u32_e32 v40, s10, v34
	v_cvt_pk_bf16_f32 v34, v2, v6
	v_lshrrev_b32_e32 v2, 8, v40
	s_ashr_i32 s17, s16, 31
	v_mul_hi_i32_i24_e32 v39, s12, v2
	v_mul_i32_i24_e32 v38, s12, v2
	v_lshl_add_u64 v[38:39], v[38:39], 0, s[16:17]
	v_lshlrev_b64 v[38:39], 15, v[38:39]
	v_lshlrev_b32_e32 v2, 7, v40
	v_lshl_add_u64 v[38:39], s[14:15], 0, v[38:39]
	v_and_b32_e32 v68, 0x7f80, v2
	v_lshl_add_u64 v[38:39], v[38:39], 0, v[68:69]
	v_mov_b32_e32 v71, v69
	v_add_u32_e32 v6, 1, v40
	v_cvt_pk_bf16_f32 v35, v10, v14
	v_cvt_pk_bf16_f32 v36, v18, v22
	v_cvt_pk_bf16_f32 v37, v26, v30
	v_lshl_add_u64 v[38:39], v[38:39], 0, v[70:71]
	v_lshrrev_b32_e32 v2, 8, v6
	global_store_dwordx4 v[38:39], v[34:37], off sc1
	v_lshlrev_b32_e32 v6, 7, v6
	v_and_b32_e32 v68, 0x7f80, v6
	v_cvt_pk_bf16_f32 v34, v3, v7
	v_mul_hi_i32_i24_e32 v3, s12, v2
	v_mul_i32_i24_e32 v2, s12, v2
	v_lshl_add_u64 v[2:3], v[2:3], 0, s[16:17]
	v_lshlrev_b64 v[2:3], 15, v[2:3]
	v_lshl_add_u64 v[2:3], s[14:15], 0, v[2:3]
	v_lshl_add_u64 v[2:3], v[2:3], 0, v[68:69]
	v_cvt_pk_bf16_f32 v35, v11, v15
	v_cvt_pk_bf16_f32 v36, v19, v23
	v_cvt_pk_bf16_f32 v37, v27, v31
	v_lshl_add_u64 v[2:3], v[2:3], 0, v[70:71]
	v_add_u32_e32 v6, 2, v40
	global_store_dwordx4 v[2:3], v[34:37], off sc1
	v_lshrrev_b32_e32 v2, 8, v6
	v_mul_hi_i32_i24_e32 v3, s12, v2
	v_mul_i32_i24_e32 v2, s12, v2
	v_lshl_add_u64 v[2:3], v[2:3], 0, s[16:17]
	v_cvt_pk_bf16_f32 v34, v4, v8
	v_lshlrev_b64 v[2:3], 15, v[2:3]
	v_lshlrev_b32_e32 v4, 7, v6
	v_lshl_add_u64 v[2:3], s[14:15], 0, v[2:3]
	v_and_b32_e32 v68, 0x7f80, v4
	v_lshl_add_u64 v[2:3], v[2:3], 0, v[68:69]
	v_cvt_pk_bf16_f32 v35, v12, v16
	v_cvt_pk_bf16_f32 v36, v20, v24
	v_cvt_pk_bf16_f32 v37, v28, v32
	v_lshl_add_u64 v[2:3], v[2:3], 0, v[70:71]
	global_store_dwordx4 v[2:3], v[34:37], off sc1
	v_cndmask_b32_e64 v2, v73, v75, s[18:19]
	v_or_b32_e32 v2, 3, v2
	v_add_u32_e32 v8, s10, v2
	v_lshrrev_b32_e32 v2, 8, v8
	v_mul_hi_i32_i24_e32 v3, s12, v2
	v_mul_i32_i24_e32 v2, s12, v2
	v_lshl_add_u64 v[6:7], v[2:3], 0, s[16:17]
	v_lshlrev_b64 v[6:7], 15, v[6:7]
	v_lshlrev_b32_e32 v8, 7, v8
	v_lshl_add_u64 v[6:7], s[14:15], 0, v[6:7]
	v_and_b32_e32 v68, 0x7f80, v8
	s_add_i32 s28, s28, s30
	s_add_i32 s31, s31, s30
	v_lshl_add_u64 v[6:7], v[6:7], 0, v[68:69]
	s_add_i32 s34, s28, s29
	s_add_i32 s10, s33, s31
	v_cvt_pk_bf16_f32 v2, v5, v9
	v_cvt_pk_bf16_f32 v3, v13, v17
	v_cvt_pk_bf16_f32 v4, v21, v25
	v_cvt_pk_bf16_f32 v5, v29, v33
	v_lshl_add_u64 v[6:7], v[6:7], 0, v[70:71]
	s_cmpk_lt_i32 s10, 0x2e00
	v_readlane_b32 s10, v254, 9
	global_store_dwordx4 v[6:7], v[2:5], off sc1
	s_cbranch_scc0 .LBB0_297

.LBB0_288:
	v_cndmask_b32_e64 v68, v74, v75, s[44:45]
	v_add_u32_e32 v82, s10, v68
	s_waitcnt vmcnt(0)
	v_cvt_pk_bf16_f32 v76, v34, v38
	v_lshrrev_b32_e32 v34, 8, v82
	s_ashr_i32 s27, s26, 31
	v_mul_hi_i32_i24_e32 v71, s20, v34
	v_mul_i32_i24_e32 v70, s20, v34
	v_lshl_add_u64 v[70:71], v[70:71], 0, s[26:27]
	v_lshlrev_b64 v[70:71], 15, v[70:71]
	v_lshlrev_b32_e32 v34, 7, v82
	v_lshl_add_u64 v[70:71], s[18:19], 0, v[70:71]
	v_and_b32_e32 v68, 0x7f80, v34
	v_lshl_add_u64 v[80:81], v[70:71], 0, v[68:69]
	v_lshlrev_b32_e32 v70, 1, v72
	v_mov_b32_e32 v71, v69
	v_add_u32_e32 v38, 1, v82
	v_cvt_pk_bf16_f32 v77, v42, v46
	v_cvt_pk_bf16_f32 v78, v50, v54
	v_cvt_pk_bf16_f32 v79, v58, v62
	v_lshl_add_u64 v[80:81], v[80:81], 0, v[70:71]
	v_lshrrev_b32_e32 v34, 8, v38
	global_store_dwordx4 v[80:81], v[76:79], off sc1
	v_lshlrev_b32_e32 v38, 7, v38
	v_and_b32_e32 v68, 0x7f80, v38
	v_cvt_pk_bf16_f32 v76, v35, v39
	v_mul_hi_i32_i24_e32 v35, s20, v34
	v_mul_i32_i24_e32 v34, s20, v34
	v_lshl_add_u64 v[34:35], v[34:35], 0, s[26:27]
	v_lshlrev_b64 v[34:35], 15, v[34:35]
	v_lshl_add_u64 v[34:35], s[18:19], 0, v[34:35]
	v_lshl_add_u64 v[34:35], v[34:35], 0, v[68:69]
	v_cvt_pk_bf16_f32 v77, v43, v47
	v_cvt_pk_bf16_f32 v78, v51, v55
	v_cvt_pk_bf16_f32 v79, v59, v63
	v_lshl_add_u64 v[34:35], v[34:35], 0, v[70:71]
	v_add_u32_e32 v38, 2, v82
	global_store_dwordx4 v[34:35], v[76:79], off sc1
	v_lshrrev_b32_e32 v34, 8, v38
	v_mul_hi_i32_i24_e32 v35, s20, v34
	v_mul_i32_i24_e32 v34, s20, v34
	v_lshl_add_u64 v[34:35], v[34:35], 0, s[26:27]
	v_cvt_pk_bf16_f32 v76, v36, v40
	v_lshlrev_b64 v[34:35], 15, v[34:35]
	v_lshlrev_b32_e32 v36, 7, v38
	v_lshl_add_u64 v[34:35], s[18:19], 0, v[34:35]
	v_and_b32_e32 v68, 0x7f80, v36
	v_lshl_add_u64 v[34:35], v[34:35], 0, v[68:69]
	v_cvt_pk_bf16_f32 v77, v44, v48
	v_cvt_pk_bf16_f32 v78, v52, v56
	v_cvt_pk_bf16_f32 v79, v60, v64
	v_lshl_add_u64 v[34:35], v[34:35], 0, v[70:71]
	global_store_dwordx4 v[34:35], v[76:79], off sc1
	v_cndmask_b32_e64 v34, v73, v75, s[44:45]
	v_or_b32_e32 v34, 3, v34
	v_add_u32_e32 v40, s10, v34
	v_lshrrev_b32_e32 v34, 8, v40
	v_mul_hi_i32_i24_e32 v35, s20, v34
	v_mul_i32_i24_e32 v34, s20, v34
	v_lshl_add_u64 v[38:39], v[34:35], 0, s[26:27]
	v_lshlrev_b64 v[38:39], 15, v[38:39]
	v_lshlrev_b32_e32 v40, 7, v40
	v_lshl_add_u64 v[38:39], s[18:19], 0, v[38:39]
	v_and_b32_e32 v68, 0x7f80, v40
	v_lshl_add_u64 v[38:39], v[38:39], 0, v[68:69]
	v_cvt_pk_bf16_f32 v34, v37, v41
	v_cvt_pk_bf16_f32 v35, v45, v49
	v_cvt_pk_bf16_f32 v36, v53, v57
	v_cvt_pk_bf16_f32 v37, v61, v65
	v_lshl_add_u64 v[38:39], v[38:39], 0, v[70:71]
	s_cmp_lt_i32 s35, 2
	s_mov_b64 s[20:21], -1
	global_store_dwordx4 v[38:39], v[34:37], off sc1
	s_cbranch_scc1 .LBB0_294
	s_cmp_gt_i32 s35, 2
	s_cbranch_scc0 .LBB0_291
	s_cmpk_lt_i32 s13, 0x80
	s_cselect_b64 s[18:19], -1, 0
	s_and_b32 s10, s34, 3
	s_cmp_eq_u32 s10, 0
	s_cselect_b64 s[20:21], -1, 0
	s_and_b64 s[18:19], s[20:21], s[18:19]
	s_mov_b64 s[20:21], 0

.LBB0_302:
	s_lshr_b32 s7, s16, 5
	v_cvt_f32_ubyte0_e32 v2, s7
	v_rcp_iflag_f32_e32 v2, v2
	s_sub_i32 s14, 0, s7
	s_abs_i32 s11, s28
	s_ashr_i32 s6, s28, 31
	v_mul_f32_e32 v2, 0x4f7ffffe, v2
	v_cvt_u32_f32_e32 v2, v2
	v_mov_b32_e32 v67, 0
	s_mov_b32 s17, 0
	v_mov_b32_e32 v35, v67
	v_readfirstlane_b32 s15, v2
	s_mul_i32 s14, s14, s15
	s_mul_hi_u32 s14, s15, s14
	s_add_i32 s15, s15, s14
	s_mul_hi_u32 s14, s11, s15
	s_mul_i32 s15, s14, s7
	s_sub_i32 s11, s11, s15
	s_add_i32 s18, s14, 1
	s_sub_i32 s15, s11, s7
	s_cmp_ge_u32 s11, s7
	s_cselect_b32 s14, s18, s14
	s_cselect_b32 s11, s15, s11
	s_add_i32 s15, s14, 1
	s_cmp_ge_u32 s11, s7
	s_cselect_b32 s11, s15, s14
	s_xor_b32 s11, s11, s6
	s_sub_i32 s6, s11, s6
	s_mul_i32 s7, s6, s7
	s_sub_i32 s7, s28, s7
	v_lshl_or_b32 v2, s6, 6, v72
	s_lshl_b32 s14, s7, 5
	v_mad_i64_i32 v[2:3], s[18:19], v2, s16, 0
	v_lshl_add_u64 v[2:3], v[2:3], 2, s[22:23]
	s_ashr_i32 s15, s14, 31
	v_lshl_add_u64 v[2:3], s[14:15], 2, v[2:3]
	v_lshl_add_u64 v[2:3], v[2:3], 0, v[66:67]
	s_lshl_b32 s16, s16, 2
	v_lshl_add_u64 v[10:11], v[2:3], 0, s[16:17]
	global_load_dwordx4 v[2:5], v[2:3], off nt
	s_nop 0
	global_load_dwordx4 v[6:9], v[10:11], off nt
	v_lshl_add_u64 v[10:11], v[10:11], 0, s[16:17]
	v_lshl_add_u64 v[18:19], v[10:11], 0, s[16:17]
	global_load_dwordx4 v[10:13], v[10:11], off nt
	s_nop 0
	global_load_dwordx4 v[14:17], v[18:19], off nt
	v_lshl_add_u64 v[18:19], v[18:19], 0, s[16:17]
	v_lshl_add_u64 v[26:27], v[18:19], 0, s[16:17]
	global_load_dwordx4 v[18:21], v[18:19], off nt
	s_nop 0
	global_load_dwordx4 v[22:25], v[26:27], off nt
	v_lshl_add_u64 v[26:27], v[26:27], 0, s[16:17]
	v_lshl_add_u64 v[30:31], v[26:27], 0, s[16:17]
	global_load_dwordx4 v[26:29], v[26:27], off nt
	s_nop 0
	global_load_dwordx4 v[30:33], v[30:31], off nt
	s_cmpk_lt_i32 s7, 0x80
	s_cselect_b64 s[16:17], -1, 0
	s_and_b32 s7, s28, 3
	s_cmp_eq_u32 s7, 0
	s_cselect_b64 s[18:19], -1, 0
	s_and_b64 s[16:17], s[18:19], s[16:17]
	s_and_b64 vcc, s[12:13], s[16:17]
	v_cndmask_b32_e32 v34, v74, v75, vcc
	v_add_u32_e32 v34, s14, v34
	v_lshlrev_b32_e32 v40, 7, v34
	v_add_u32_e32 v41, 1, v34
	v_lshrrev_b32_e32 v38, 8, v34
	v_add_u32_e32 v34, 2, v34
	v_and_b32_e32 v66, 0x7f80, v40
	v_lshrrev_b32_e32 v40, 8, v41
	s_ashr_i32 s7, s6, 31
	v_cndmask_b32_e32 v36, v73, v75, vcc
	v_mul_hi_i32_i24_e32 v39, s10, v38
	v_mul_i32_i24_e32 v38, s10, v38
	v_lshlrev_b32_e32 v42, 7, v41
	v_lshrrev_b32_e32 v44, 8, v34
	v_mul_hi_i32_i24_e32 v41, s10, v40
	v_mul_i32_i24_e32 v40, s10, v40
	v_or_b32_e32 v36, 3, v36
	v_lshlrev_b32_e32 v45, 7, v34
	v_lshl_add_u64 v[38:39], v[38:39], 0, s[6:7]
	v_and_b32_e32 v34, 0x7f80, v42
	v_mul_hi_i32_i24_e32 v43, s10, v44
	v_mul_i32_i24_e32 v42, s10, v44
	v_lshl_add_u64 v[40:41], v[40:41], 0, s[6:7]
	v_add_u32_e32 v48, s14, v36
	v_lshlrev_b64 v[38:39], 15, v[38:39]
	v_lshl_add_u64 v[42:43], v[42:43], 0, s[6:7]
	v_lshlrev_b64 v[40:41], 15, v[40:41]
	v_lshrrev_b32_e32 v44, 8, v48
	v_lshl_add_u64 v[38:39], s[0:1], 0, v[38:39]
	v_lshlrev_b64 v[42:43], 15, v[42:43]
	v_lshl_add_u64 v[40:41], s[0:1], 0, v[40:41]
	v_mov_b32_e32 v37, v67
	v_and_b32_e32 v36, 0x7f80, v45
	v_mul_hi_i32_i24_e32 v45, s10, v44
	v_mul_i32_i24_e32 v44, s10, v44
	v_lshl_add_u64 v[38:39], v[38:39], 0, v[66:67]
	v_lshlrev_b32_e32 v66, 1, v72
	v_lshl_add_u64 v[42:43], s[0:1], 0, v[42:43]
	v_lshl_add_u64 v[34:35], v[40:41], 0, v[34:35]
	v_lshl_add_u64 v[44:45], v[44:45], 0, s[6:7]
	v_lshl_add_u64 v[46:47], v[38:39], 0, v[66:67]
	v_lshl_add_u64 v[36:37], v[42:43], 0, v[36:37]
	v_lshl_add_u64 v[40:41], v[34:35], 0, v[66:67]
	v_lshl_add_u64 v[42:43], v[36:37], 0, v[66:67]
	s_waitcnt vmcnt(0)
	v_cvt_pk_bf16_f32 v2, v2, v6
	v_cvt_pk_bf16_f32 v6, v3, v7
	v_cvt_pk_bf16_f32 v34, v4, v8
	v_cvt_pk_bf16_f32 v38, v5, v9
	v_cvt_pk_bf16_f32 v3, v10, v14
	v_cvt_pk_bf16_f32 v7, v11, v15
	v_cvt_pk_bf16_f32 v4, v18, v22
	v_cvt_pk_bf16_f32 v35, v12, v16
	v_cvt_pk_bf16_f32 v8, v19, v23
	v_cvt_pk_bf16_f32 v5, v26, v30
	v_cvt_pk_bf16_f32 v36, v20, v24
	v_cvt_pk_bf16_f32 v9, v27, v31
	v_cvt_pk_bf16_f32 v37, v28, v32
	global_store_dwordx4 v[46:47], v[2:5], off sc1
	global_store_dwordx4 v[40:41], v[6:9], off sc1
	global_store_dwordx4 v[42:43], v[34:37], off sc1
	v_lshlrev_b64 v[2:3], 15, v[44:45]
	v_lshlrev_b32_e32 v4, 7, v48
	v_lshl_add_u64 v[2:3], s[0:1], 0, v[2:3]
	v_and_b32_e32 v4, 0x7f80, v4
	v_mov_b32_e32 v5, v67
	v_lshl_add_u64 v[2:3], v[2:3], 0, v[4:5]
	v_cvt_pk_bf16_f32 v39, v13, v17
	v_cvt_pk_bf16_f32 v40, v21, v25
	v_cvt_pk_bf16_f32 v41, v29, v33
	v_lshl_add_u64 v[2:3], v[2:3], 0, v[66:67]
	global_store_dwordx4 v[2:3], v[38:41], off sc1
.Lmy_td2:
	s_waitcnt vmcnt(0)
	s_mov_b64 s[6:7], exec
	s_mov_b64 exec, 1
	v_mov_b32_e32 v2, 0x34800
	v_mov_b32_e32 v3, 1
	global_atomic_add v2, v3, s[50:51]
	s_mov_b64 exec, s[6:7]
.LBB0_303:
	v_readlane_b32 s0, v254, 0
	v_readlane_b32 s1, v254, 1
	s_cmp_gt_i32 s1, 3
	s_cselect_b64 s[0:1], -1, 0
	s_and_b64 s[4:5], s[4:5], s[0:1]
	s_andn2_b64 vcc, exec, s[4:5]
	s_cbranch_vccnz .LBB0_357
	s_waitcnt vmcnt(0)
	s_waitcnt vmcnt(0) lgkmcnt(0)
	s_barrier
	s_mov_b64 s[4:5], exec
	v_readlane_b32 s6, v254, 7
	v_readlane_b32 s7, v254, 8
	s_and_b64 s[6:7], s[4:5], s[6:7]
	s_mov_b64 exec, s[6:7]
	s_cbranch_execz .Lmy_cv2_entry
	s_cmpk_lg_i32 s3, 0x100
	s_cbranch_scc1 .Lmy_gb2_orig
	s_and_b32 s6, s2, 7
	s_lshl_b32 s6, s6, 6
	s_add_u32 s6, s6, 0x33800
	v_mov_b32_e32 v2, s6
	v_mov_b32_e32 v3, 1
	global_atomic_add v2, v3, s[50:51]
	s_movk_i32 s7, 0x4000

.Lmy_gb2_go:
	v_mov_b32_e32 v2, 0x34800
	s_movk_i32 s7, 0x4000
.Lmy_gb2_tspin:
	global_load_dword v4, v2, s[50:51] sc1
	s_waitcnt vmcnt(0)
	v_cmp_gt_u32_e32 vcc, 0x400, v4
	s_cbranch_vccz .Lmy_gb2_tgo
	s_sleep 1
	s_sub_u32 s7, s7, 1
	s_cmp_lg_u32 s7, 0
	s_cbranch_scc1 .Lmy_gb2_tspin

.Lmy_gb2_orig:
	s_add_i32 s6, 0, 0x23fc0
	v_mov_b32_e32 v2, s6
	s_waitcnt vmcnt(0) expcnt(0) lgkmcnt(0)
	ds_read_b32 v4, v2
	s_add_i32 s6, 0, 0x23fc4
	v_mov_b32_e32 v2, s6
	ds_read_b32 v2, v2
	s_waitcnt lgkmcnt(1)
	v_cmp_ne_u32_e32 vcc, 0, v4
	s_cbranch_vccnz .LBB0_320
	v_readlane_b32 s6, v254, 2
	v_readlane_b32 s7, v254, 3
	s_load_dwordx2 s[12:13], s[6:7], 0x4
	s_add_u32 s6, s50, 0x28200
	s_addc_u32 s7, s51, 0
	s_add_u32 s10, s50, 0x28400
	s_addc_u32 s11, s51, 0
	s_waitcnt lgkmcnt(0)
	s_mul_i32 s28, s12, s3
	s_add_u32 s12, s50, 0x28500
	s_mul_i32 s28, s28, s13
	s_addc_u32 s13, s51, 0
	s_add_u32 s14, s50, 0x28600
	s_addc_u32 s15, s51, 0
	s_add_u32 s16, s50, 0x28700
	s_addc_u32 s17, s51, 0
	s_add_u32 s18, s50, 0x28800
	s_addc_u32 s19, s51, 0
	s_add_u32 s20, s50, 0x28900
	s_addc_u32 s21, s51, 0
	s_add_u32 s22, s50, 0x28a00
	s_addc_u32 s23, s51, 0
	s_add_u32 s24, s50, 0x28b00
	s_addc_u32 s25, s51, 0
	s_add_u32 s26, s50, 0x28c00
	s_addc_u32 s27, s51, 0
	s_add_u32 s42, s50, 0x28d00
	s_addc_u32 s43, s51, 0
	s_add_u32 s44, s50, 0x28e00
	s_addc_u32 s45, s51, 0
	s_add_u32 s54, s50, 0x28f00
	s_addc_u32 s55, s51, 0
	s_add_u32 s56, s50, 0x29000
	s_addc_u32 s57, s51, 0
	s_add_u32 s58, s50, 0x29100
	s_addc_u32 s59, s51, 0
	s_add_u32 s60, s50, 0x29200
	s_addc_u32 s61, s51, 0
	s_add_u32 s62, s50, 0x29300
	s_addc_u32 s63, s51, 0
	s_mov_b32 s29, 1
	v_mov_b32_e32 v18, 0
	s_branch .LBB0_308

.LBB0_989:
	s_lshl_b32 s13, s20, 8
	s_add_i32 s13, s13, s44
	s_lshl_b32 s15, s21, 7
	v_or_b32_e32 v155, s13, v150
	s_or_b32 s15, s15, s45
	s_ashr_i32 s13, s13, 8
	s_ashr_i32 s20, s15, 6
	s_mulk_i32 s13, 0x58
	s_ashr_i32 s21, s20, 31
	s_ashr_i32 s15, s13, 31
	s_add_u32 s22, s13, s20
	s_addc_u32 s23, s15, s21
	s_lshl_b64 s[22:23], s[22:23], 15
	s_add_u32 s22, s38, s22
	v_lshlrev_b32_e32 v138, 7, v155
	s_addc_u32 s23, s39, s23
	v_and_b32_e32 v138, 0x6780, v138
	v_lshl_add_u64 v[156:157], s[22:23], 0, v[138:139]
	v_mul_f32_e32 v138, 0xbfb8aa3b, v126
	v_exp_f32_e32 v138, v138
	v_mul_f32_e32 v149, 0xbfb8aa3b, v127
	v_exp_f32_e32 v158, v149
	v_mov_b32_e32 v149, v139
	v_add_f32_e32 v138, 1.0, v138
	v_rcp_f32_e32 v138, v138
	v_add_f32_e32 v158, 1.0, v158
	v_rcp_f32_e32 v158, v158
	v_lshl_add_u64 v[156:157], v[156:157], 0, v[148:149]
	v_mul_f32_e32 v126, v126, v138
	v_mul_f32_e32 v118, v126, v118
	v_mul_f32_e32 v126, v127, v158
	v_mul_f32_e32 v127, 0xbfb8aa3b, v128
	v_exp_f32_e32 v127, v127
	v_mul_f32_e32 v138, 0xbfb8aa3b, v129
	v_exp_f32_e32 v138, v138
	v_mul_f32_e32 v119, v126, v119
	v_add_f32_e32 v126, 1.0, v127
	v_rcp_f32_e32 v126, v126
	v_add_f32_e32 v127, 1.0, v138
	v_rcp_f32_e32 v127, v127
	v_cvt_pk_bf16_f32 v118, v118, v119
	v_mul_f32_e32 v119, v128, v126
	v_mul_f32_e32 v126, 0xbfb8aa3b, v122
	v_exp_f32_e32 v126, v126
	v_mul_f32_e32 v119, v119, v120
	v_mul_f32_e32 v120, v129, v127
	v_mul_f32_e32 v127, 0xbfb8aa3b, v123
	v_exp_f32_e32 v127, v127
	v_mul_f32_e32 v120, v120, v121
	v_add_f32_e32 v121, 1.0, v126
	v_rcp_f32_e32 v121, v121
	v_add_f32_e32 v126, 1.0, v127
	v_rcp_f32_e32 v126, v126
	v_cvt_pk_bf16_f32 v119, v119, v120
	v_mul_f32_e32 v120, v122, v121
	v_mul_f32_e32 v121, 0xbfb8aa3b, v124
	v_exp_f32_e32 v121, v121
	v_mul_f32_e32 v122, 0xbfb8aa3b, v125
	v_exp_f32_e32 v122, v122
	v_mul_f32_e32 v114, v120, v114
	v_mul_f32_e32 v120, v123, v126
	v_mul_f32_e32 v115, v120, v115
	v_add_f32_e32 v120, 1.0, v121
	v_rcp_f32_e32 v121, v120
	v_add_f32_e32 v120, 1.0, v122
	v_rcp_f32_e32 v122, v120
	v_cvt_pk_bf16_f32 v120, v114, v115
	v_mul_f32_e32 v114, v124, v121
	v_mul_f32_e32 v114, v114, v116
	v_mul_f32_e32 v115, v125, v122
	v_mul_f32_e32 v116, 0xbfb8aa3b, v110
	v_mul_f32_e32 v115, v115, v117
	v_exp_f32_e32 v116, v116
	v_mul_f32_e32 v117, 0xbfb8aa3b, v111
	v_exp_f32_e32 v117, v117
	v_cvt_pk_bf16_f32 v121, v114, v115
	v_add_f32_e32 v114, 1.0, v116
	v_rcp_f32_e32 v114, v114
	v_add_f32_e32 v115, 1.0, v117
	v_rcp_f32_e32 v115, v115
	global_store_dwordx4 v[156:157], v[118:121], off sc1
	v_mul_f32_e32 v110, v110, v114
	v_mul_f32_e32 v102, v110, v102
	v_mul_f32_e32 v110, v111, v115
	v_mul_f32_e32 v111, 0xbfb8aa3b, v112
	v_exp_f32_e32 v111, v111
	v_mul_f32_e32 v114, 0xbfb8aa3b, v113
	v_exp_f32_e32 v114, v114
	v_mul_f32_e32 v103, v110, v103
	v_add_f32_e32 v110, 1.0, v111
	v_rcp_f32_e32 v110, v110
	v_add_f32_e32 v111, 1.0, v114
	v_rcp_f32_e32 v111, v111
	v_cvt_pk_bf16_f32 v102, v102, v103
	v_mul_f32_e32 v103, v112, v110
	v_mul_f32_e32 v110, 0xbfb8aa3b, v106
	v_exp_f32_e32 v110, v110
	v_mul_f32_e32 v103, v103, v104
	v_mul_f32_e32 v104, v113, v111
	v_mul_f32_e32 v111, 0xbfb8aa3b, v107
	v_exp_f32_e32 v111, v111
	v_mul_f32_e32 v104, v104, v105
	v_add_f32_e32 v105, 1.0, v110
	v_rcp_f32_e32 v105, v105
	v_add_f32_e32 v110, 1.0, v111
	v_rcp_f32_e32 v110, v110
	v_cvt_pk_bf16_f32 v103, v103, v104
	v_mul_f32_e32 v104, v106, v105
	v_mul_f32_e32 v105, 0xbfb8aa3b, v108
	v_exp_f32_e32 v105, v105
	v_mul_f32_e32 v106, 0xbfb8aa3b, v109
	v_exp_f32_e32 v106, v106
	v_mul_f32_e32 v98, v104, v98
	v_mul_f32_e32 v104, v107, v110
	v_mul_f32_e32 v99, v104, v99
	v_add_f32_e32 v104, 1.0, v105
	v_rcp_f32_e32 v105, v104
	v_add_f32_e32 v104, 1.0, v106
	v_rcp_f32_e32 v106, v104
	v_cvt_pk_bf16_f32 v104, v98, v99
	v_mul_f32_e32 v98, v108, v105
	v_mul_f32_e32 v98, v98, v100
	v_mul_f32_e32 v99, v109, v106
	v_mul_f32_e32 v100, 0xbfb8aa3b, v94
	v_mul_f32_e32 v99, v99, v101
	v_exp_f32_e32 v100, v100
	v_mul_f32_e32 v101, 0xbfb8aa3b, v95
	v_exp_f32_e32 v101, v101
	v_cvt_pk_bf16_f32 v105, v98, v99
	v_add_f32_e32 v98, 1.0, v100
	v_rcp_f32_e32 v98, v98
	v_add_f32_e32 v99, 1.0, v101
	v_rcp_f32_e32 v99, v99
	global_store_dwordx4 v[156:157], v[102:105], off offset:2048 sc1
	v_mul_f32_e32 v94, v94, v98
	v_mul_f32_e32 v86, v94, v86
	v_mul_f32_e32 v94, v95, v99
	v_mul_f32_e32 v95, 0xbfb8aa3b, v96
	v_exp_f32_e32 v95, v95
	v_mul_f32_e32 v98, 0xbfb8aa3b, v97
	v_exp_f32_e32 v98, v98
	v_mul_f32_e32 v87, v94, v87
	v_add_f32_e32 v94, 1.0, v95
	v_rcp_f32_e32 v94, v94
	v_add_f32_e32 v95, 1.0, v98
	v_rcp_f32_e32 v95, v95
	v_cvt_pk_bf16_f32 v86, v86, v87
	v_mul_f32_e32 v87, v96, v94
	v_mul_f32_e32 v94, 0xbfb8aa3b, v90
	v_exp_f32_e32 v94, v94
	v_mul_f32_e32 v87, v87, v88
	v_mul_f32_e32 v88, v97, v95
	v_mul_f32_e32 v95, 0xbfb8aa3b, v91
	v_exp_f32_e32 v95, v95
	v_mul_f32_e32 v88, v88, v89
	v_add_f32_e32 v89, 1.0, v94
	v_rcp_f32_e32 v89, v89
	v_add_f32_e32 v94, 1.0, v95
	v_rcp_f32_e32 v94, v94
	v_cvt_pk_bf16_f32 v87, v87, v88
	v_mul_f32_e32 v88, v90, v89
	v_mul_f32_e32 v89, 0xbfb8aa3b, v92
	v_exp_f32_e32 v89, v89
	v_mul_f32_e32 v90, 0xbfb8aa3b, v93
	v_exp_f32_e32 v90, v90
	v_mul_f32_e32 v82, v88, v82
	v_mul_f32_e32 v88, v91, v94
	v_mul_f32_e32 v83, v88, v83
	v_add_f32_e32 v88, 1.0, v89
	v_rcp_f32_e32 v89, v88
	v_add_f32_e32 v88, 1.0, v90
	v_rcp_f32_e32 v90, v88
	v_cvt_pk_bf16_f32 v88, v82, v83
	v_mul_f32_e32 v82, v92, v89
	v_mul_f32_e32 v82, v82, v84
	v_mul_f32_e32 v83, v93, v90
	v_mul_f32_e32 v83, v83, v85
	v_cvt_pk_bf16_f32 v89, v82, v83
	v_mul_f32_e32 v82, 0xbfb8aa3b, v78
	v_exp_f32_e32 v84, v82
	v_mul_f32_e32 v82, 0xbfb8aa3b, v79
	v_exp_f32_e32 v85, v82
	v_add_co_u32_e32 v82, vcc, s57, v156
	v_add_f32_e32 v84, 1.0, v84
	v_rcp_f32_e32 v84, v84
	v_add_f32_e32 v85, 1.0, v85
	v_rcp_f32_e32 v85, v85
	v_addc_co_u32_e32 v83, vcc, 0, v157, vcc
	v_mul_f32_e32 v78, v78, v84
	v_mul_f32_e32 v70, v78, v70
	v_mul_f32_e32 v78, v79, v85
	v_mul_f32_e32 v79, 0xbfb8aa3b, v80
	v_exp_f32_e32 v79, v79
	v_mul_f32_e32 v84, 0xbfb8aa3b, v81
	v_exp_f32_e32 v84, v84
	v_mul_f32_e32 v71, v78, v71
	v_add_f32_e32 v78, 1.0, v79
	v_rcp_f32_e32 v78, v78
	v_add_f32_e32 v79, 1.0, v84
	global_store_dwordx4 v[82:83], v[86:89], off sc1
	v_rcp_f32_e32 v79, v79
	v_cvt_pk_bf16_f32 v70, v70, v71
	v_mul_f32_e32 v71, v80, v78
	v_mul_f32_e32 v78, 0xbfb8aa3b, v74
	v_exp_f32_e32 v78, v78
	v_mul_f32_e32 v71, v71, v72
	v_mul_f32_e32 v72, v81, v79
	v_mul_f32_e32 v79, 0xbfb8aa3b, v75
	v_exp_f32_e32 v79, v79
	v_mul_f32_e32 v72, v72, v73
	v_add_f32_e32 v73, 1.0, v78
	v_rcp_f32_e32 v73, v73
	v_add_f32_e32 v78, 1.0, v79
	v_rcp_f32_e32 v78, v78
	v_cvt_pk_bf16_f32 v71, v71, v72
	v_mul_f32_e32 v72, v74, v73
	v_mul_f32_e32 v73, 0xbfb8aa3b, v76
	v_exp_f32_e32 v73, v73
	v_mul_f32_e32 v74, 0xbfb8aa3b, v77
	v_exp_f32_e32 v74, v74
	v_mul_f32_e32 v66, v72, v66
	v_mul_f32_e32 v72, v75, v78
	v_mul_f32_e32 v67, v72, v67
	v_add_f32_e32 v72, 1.0, v73
	v_rcp_f32_e32 v73, v72
	v_add_f32_e32 v72, 1.0, v74
	v_rcp_f32_e32 v74, v72
	v_cvt_pk_bf16_f32 v72, v66, v67
	v_mul_f32_e32 v66, v76, v73
	v_mul_f32_e32 v66, v66, v68
	v_mul_f32_e32 v67, v77, v74
	v_add_u32_e32 v68, 0x80, v155
	v_mul_f32_e32 v67, v67, v69
	v_cvt_pk_bf16_f32 v73, v66, v67
	v_lshrrev_b32_e32 v66, 8, v68
	v_lshlrev_b32_e32 v68, 7, v68
	v_and_b32_e32 v138, 0x6780, v68
	v_mul_f32_e32 v68, 0xbfb8aa3b, v62
	v_exp_f32_e32 v68, v68
	v_mul_f32_e32 v69, 0xbfb8aa3b, v63
	v_exp_f32_e32 v69, v69
	global_store_dwordx4 v[82:83], v[70:73], off offset:2048 sc1
	v_add_f32_e32 v68, 1.0, v68
	v_rcp_f32_e32 v68, v68
	v_add_f32_e32 v69, 1.0, v69
	v_rcp_f32_e32 v69, v69
	v_mul_i32_i24_e32 v66, 0x58, v66
	v_mul_f32_e32 v62, v62, v68
	v_mul_f32_e32 v54, v62, v54
	v_mul_f32_e32 v62, v63, v69
	v_mul_f32_e32 v63, 0xbfb8aa3b, v64
	v_exp_f32_e32 v63, v63
	v_mul_f32_e32 v68, 0xbfb8aa3b, v65
	v_exp_f32_e32 v68, v68
	v_mul_f32_e32 v55, v62, v55
	v_add_f32_e32 v62, 1.0, v63
	v_rcp_f32_e32 v62, v62
	v_add_f32_e32 v63, 1.0, v68
	v_rcp_f32_e32 v63, v63
	v_cvt_pk_bf16_f32 v54, v54, v55
	v_mul_f32_e32 v55, v64, v62
	v_mul_f32_e32 v62, 0xbfb8aa3b, v58
	v_exp_f32_e32 v62, v62
	v_mul_f32_e32 v55, v55, v56
	v_mul_f32_e32 v56, v65, v63
	v_mul_f32_e32 v63, 0xbfb8aa3b, v59
	v_exp_f32_e32 v63, v63
	v_mul_f32_e32 v56, v56, v57
	v_add_f32_e32 v57, 1.0, v62
	v_rcp_f32_e32 v57, v57
	v_add_f32_e32 v62, 1.0, v63
	v_rcp_f32_e32 v62, v62
	v_cvt_pk_bf16_f32 v55, v55, v56
	v_mul_f32_e32 v56, v58, v57
	v_mul_f32_e32 v57, 0xbfb8aa3b, v60
	v_exp_f32_e32 v57, v57
	v_mul_f32_e32 v58, 0xbfb8aa3b, v61
	v_exp_f32_e32 v58, v58
	v_mul_f32_e32 v50, v56, v50
	v_mul_f32_e32 v56, v59, v62
	v_mul_f32_e32 v51, v56, v51
	v_add_f32_e32 v56, 1.0, v57
	v_rcp_f32_e32 v57, v56
	v_add_f32_e32 v56, 1.0, v58
	v_rcp_f32_e32 v58, v56
	v_cvt_pk_bf16_f32 v56, v50, v51
	v_mul_f32_e32 v50, v60, v57
	v_mul_f32_e32 v50, v50, v52
	v_mul_f32_e32 v51, v61, v58
	v_mul_f32_e32 v52, 0xbfb8aa3b, v46
	v_mul_f32_e32 v51, v51, v53
	v_exp_f32_e32 v52, v52
	v_mul_f32_e32 v53, 0xbfb8aa3b, v47
	v_exp_f32_e32 v53, v53
	v_cvt_pk_bf16_f32 v57, v50, v51
	v_add_f32_e32 v50, 1.0, v52
	v_rcp_f32_e32 v50, v50
	v_add_f32_e32 v51, 1.0, v53
	v_rcp_f32_e32 v51, v51
	v_ashrrev_i32_e32 v67, 31, v66
	v_mul_f32_e32 v46, v46, v50
	v_mul_f32_e32 v38, v46, v38
	v_mul_f32_e32 v46, v47, v51
	v_mul_f32_e32 v47, 0xbfb8aa3b, v48
	v_exp_f32_e32 v47, v47
	v_mul_f32_e32 v50, 0xbfb8aa3b, v49
	v_lshl_add_u64 v[66:67], v[66:67], 0, s[20:21]
	v_exp_f32_e32 v50, v50
	v_mul_f32_e32 v39, v46, v39
	v_add_f32_e32 v46, 1.0, v47
	v_lshlrev_b64 v[66:67], 15, v[66:67]
	v_rcp_f32_e32 v46, v46
	v_lshl_add_u64 v[66:67], s[38:39], 0, v[66:67]
	v_lshl_add_u64 v[66:67], v[66:67], 0, v[138:139]
	v_lshl_add_u64 v[66:67], v[66:67], 0, v[148:149]
	v_add_f32_e32 v47, 1.0, v50
	global_store_dwordx4 v[66:67], v[54:57], off sc1
	v_rcp_f32_e32 v47, v47
	v_cvt_pk_bf16_f32 v38, v38, v39
	v_mul_f32_e32 v39, v48, v46
	v_mul_f32_e32 v46, 0xbfb8aa3b, v42
	v_exp_f32_e32 v46, v46
	v_mul_f32_e32 v39, v39, v40
	v_mul_f32_e32 v40, v49, v47
	v_mul_f32_e32 v47, 0xbfb8aa3b, v43
	v_exp_f32_e32 v47, v47
	v_mul_f32_e32 v40, v40, v41
	v_add_f32_e32 v41, 1.0, v46
	v_rcp_f32_e32 v41, v41
	v_add_f32_e32 v46, 1.0, v47
	v_rcp_f32_e32 v46, v46
	v_cvt_pk_bf16_f32 v39, v39, v40
	v_mul_f32_e32 v40, v42, v41
	v_mul_f32_e32 v41, 0xbfb8aa3b, v44
	v_exp_f32_e32 v41, v41
	v_mul_f32_e32 v42, 0xbfb8aa3b, v45
	v_exp_f32_e32 v42, v42
	v_mul_f32_e32 v34, v40, v34
	v_mul_f32_e32 v40, v43, v46
	v_mul_f32_e32 v35, v40, v35
	v_add_f32_e32 v40, 1.0, v41
	v_rcp_f32_e32 v41, v40
	v_add_f32_e32 v40, 1.0, v42
	v_rcp_f32_e32 v42, v40
	v_cvt_pk_bf16_f32 v40, v34, v35
	v_mul_f32_e32 v34, v44, v41
	v_mul_f32_e32 v34, v34, v36
	v_mul_f32_e32 v35, v45, v42
	v_mul_f32_e32 v36, 0xbfb8aa3b, v30
	v_mul_f32_e32 v35, v35, v37
	v_exp_f32_e32 v36, v36
	v_mul_f32_e32 v37, 0xbfb8aa3b, v31
	v_exp_f32_e32 v37, v37
	v_cvt_pk_bf16_f32 v41, v34, v35
	v_add_f32_e32 v34, 1.0, v36
	v_rcp_f32_e32 v34, v34
	v_add_f32_e32 v35, 1.0, v37
	v_rcp_f32_e32 v35, v35
	global_store_dwordx4 v[66:67], v[38:41], off offset:2048 sc1
	v_mul_f32_e32 v30, v30, v34
	v_mul_f32_e32 v22, v30, v22
	v_mul_f32_e32 v30, v31, v35
	v_mul_f32_e32 v31, 0xbfb8aa3b, v32
	v_exp_f32_e32 v31, v31
	v_mul_f32_e32 v34, 0xbfb8aa3b, v33
	v_exp_f32_e32 v34, v34
	v_mul_f32_e32 v23, v30, v23
	v_add_f32_e32 v30, 1.0, v31
	v_rcp_f32_e32 v30, v30
	v_add_f32_e32 v31, 1.0, v34
	v_rcp_f32_e32 v31, v31
	v_cvt_pk_bf16_f32 v22, v22, v23
	v_mul_f32_e32 v23, v32, v30
	v_mul_f32_e32 v30, 0xbfb8aa3b, v26
	v_exp_f32_e32 v30, v30
	v_mul_f32_e32 v23, v23, v24
	v_mul_f32_e32 v24, v33, v31
	v_mul_f32_e32 v31, 0xbfb8aa3b, v27
	v_exp_f32_e32 v31, v31
	v_mul_f32_e32 v24, v24, v25
	v_add_f32_e32 v25, 1.0, v30
	v_rcp_f32_e32 v25, v25
	v_add_f32_e32 v30, 1.0, v31
	v_rcp_f32_e32 v30, v30
	v_cvt_pk_bf16_f32 v23, v23, v24
	v_mul_f32_e32 v24, v26, v25
	v_mul_f32_e32 v25, 0xbfb8aa3b, v28
	v_exp_f32_e32 v25, v25
	v_mul_f32_e32 v26, 0xbfb8aa3b, v29
	v_exp_f32_e32 v26, v26
	v_mul_f32_e32 v18, v24, v18
	v_mul_f32_e32 v24, v27, v30
	v_mul_f32_e32 v19, v24, v19
	v_add_f32_e32 v24, 1.0, v25
	v_rcp_f32_e32 v25, v24
	v_add_f32_e32 v24, 1.0, v26
	v_rcp_f32_e32 v26, v24
	v_cvt_pk_bf16_f32 v24, v18, v19
	v_mul_f32_e32 v18, v28, v25
	v_mul_f32_e32 v18, v18, v20
	v_mul_f32_e32 v19, v29, v26
	v_mul_f32_e32 v19, v19, v21
	v_cvt_pk_bf16_f32 v25, v18, v19
	v_mul_f32_e32 v18, 0xbfb8aa3b, v14
	v_exp_f32_e32 v20, v18
	v_mul_f32_e32 v18, 0xbfb8aa3b, v15
	v_exp_f32_e32 v21, v18
	v_add_co_u32_e32 v18, vcc, s57, v66
	v_add_f32_e32 v20, 1.0, v20
	v_rcp_f32_e32 v20, v20
	v_add_f32_e32 v21, 1.0, v21
	v_rcp_f32_e32 v21, v21
	v_addc_co_u32_e32 v19, vcc, 0, v67, vcc
	v_mul_f32_e32 v14, v14, v20
	v_mul_f32_e32 v6, v14, v6
	v_mul_f32_e32 v14, v15, v21
	v_mul_f32_e32 v15, 0xbfb8aa3b, v16
	v_exp_f32_e32 v15, v15
	v_mul_f32_e32 v20, 0xbfb8aa3b, v17
	v_exp_f32_e32 v20, v20
	v_mul_f32_e32 v7, v14, v7
	v_add_f32_e32 v14, 1.0, v15
	v_rcp_f32_e32 v14, v14
	v_add_f32_e32 v15, 1.0, v20
	global_store_dwordx4 v[18:19], v[22:25], off sc1
	v_rcp_f32_e32 v15, v15
	v_cvt_pk_bf16_f32 v6, v6, v7
	v_mul_f32_e32 v7, v16, v14
	v_mul_f32_e32 v14, 0xbfb8aa3b, v10
	v_exp_f32_e32 v14, v14
	v_mul_f32_e32 v7, v7, v8
	v_mul_f32_e32 v8, v17, v15
	v_mul_f32_e32 v15, 0xbfb8aa3b, v11
	v_exp_f32_e32 v15, v15
	v_mul_f32_e32 v8, v8, v9
	v_add_f32_e32 v9, 1.0, v14
	v_rcp_f32_e32 v9, v9
	v_add_f32_e32 v14, 1.0, v15
	v_rcp_f32_e32 v14, v14
	v_cvt_pk_bf16_f32 v7, v7, v8
	v_mul_f32_e32 v8, v10, v9
	v_mul_f32_e32 v9, 0xbfb8aa3b, v12
	v_exp_f32_e32 v9, v9
	v_mul_f32_e32 v10, 0xbfb8aa3b, v13
	v_exp_f32_e32 v10, v10
	v_mul_f32_e32 v2, v8, v2
	v_mul_f32_e32 v8, v11, v14
	v_mul_f32_e32 v3, v8, v3
	v_add_f32_e32 v8, 1.0, v9
	v_rcp_f32_e32 v9, v8
	v_add_f32_e32 v8, 1.0, v10
	v_rcp_f32_e32 v10, v8
	v_cvt_pk_bf16_f32 v8, v2, v3
	v_mul_f32_e32 v2, v12, v9
	s_andn2_b64 vcc, exec, s[0:1]
	v_mul_f32_e32 v3, v13, v10
	s_mov_b64 s[0:1], -1
	v_mul_f32_e32 v2, v2, v4
	v_mul_f32_e32 v3, v3, v5
	v_cvt_pk_bf16_f32 v9, v2, v3
	global_store_dwordx4 v[18:19], v[6:9], off offset:2048 sc1
	s_cbranch_vccnz .LBB0_982
	s_andn2_b64 vcc, exec, s[6:7]
	s_cbranch_vccnz .LBB0_981
	s_barrier
	s_branch .LBB0_981

.LBB0_996:
	s_add_i32 s23, s30, s13
	s_ashr_i32 s25, s22, 31
	s_ashr_i32 s26, s23, 31
	s_lshr_b32 s25, s25, 26
	s_lshl_b32 s24, s22, 5
	v_add_u32_e32 v18, s9, v14
	s_lshr_b32 s26, s26, 26
	s_add_i32 s22, s22, s25
	v_add_u32_e32 v17, s9, v15
	v_and_b32_e32 v98, 0x3fc0, v18
	v_or_b32_e32 v18, s24, v3
	s_add_i32 s23, s23, s26
	s_ashr_i32 s26, s22, 6
	s_andn2_b32 s22, s22, 63
	v_add_u32_e32 v19, 64, v17
	v_lshlrev_b32_e32 v100, 7, v18
	v_or_b32_e32 v18, s22, v2
	v_and_b32_e32 v99, 0x3f40, v19
	s_lshl_b32 s25, s26, 11
	v_ashrrev_i32_e32 v19, 31, v18
	v_or_b32_e32 v20, s24, v11
	s_ashr_i32 s27, s23, 6
	s_andn2_b32 s23, s23, 63
	s_sub_i32 s22, s24, s25
	v_lshlrev_b64 v[18:19], 13, v[18:19]
	v_lshlrev_b32_e32 v102, 7, v20
	v_or_b32_e32 v20, s23, v2
	s_ashr_i32 s23, s22, 31
	v_lshl_add_u64 v[18:19], s[46:47], 0, v[18:19]
	v_or_b32_e32 v22, s24, v13
	v_lshl_add_u64 v[18:19], s[22:23], 2, v[18:19]
	v_lshlrev_b32_e32 v106, 7, v22
	v_lshl_add_u64 v[22:23], v[18:19], 0, v[6:7]
	v_add_co_u32_e32 v24, vcc, s15, v22
	v_or_b32_e32 v21, s24, v12
	s_nop 0
	v_addc_co_u32_e32 v25, vcc, 0, v23, vcc
	v_add_co_u32_e32 v50, vcc, s16, v22
	v_lshlrev_b32_e32 v104, 7, v21
	s_nop 0
	v_addc_co_u32_e32 v51, vcc, 0, v23, vcc
	v_add_co_u32_e32 v52, vcc, s17, v22
	s_lshl_b32 s28, s27, 11
	s_nop 0
	v_addc_co_u32_e32 v53, vcc, 0, v23, vcc
	v_add_co_u32_e32 v54, vcc, s18, v22
	v_ashrrev_i32_e32 v21, 31, v20
	s_nop 0
	v_addc_co_u32_e32 v55, vcc, 0, v23, vcc
	v_add_co_u32_e32 v56, vcc, s19, v22
	s_sub_i32 s24, s11, s28
	s_nop 0
	v_addc_co_u32_e32 v57, vcc, 0, v23, vcc
	v_lshlrev_b64 v[20:21], 13, v[20:21]
	v_add_co_u32_e32 v58, vcc, s20, v22
	s_ashr_i32 s25, s24, 31
	v_lshl_add_u64 v[20:21], s[46:47], 0, v[20:21]
	v_addc_co_u32_e32 v59, vcc, 0, v23, vcc
	v_lshl_add_u64 v[20:21], s[24:25], 2, v[20:21]
	v_add_co_u32_e32 v60, vcc, s21, v22
	v_lshl_add_u64 v[82:83], v[20:21], 0, v[6:7]
	s_nop 0
	v_addc_co_u32_e32 v61, vcc, 0, v23, vcc
	v_add_co_u32_e32 v84, vcc, s15, v82
	global_load_dwordx4 v[18:21], v[22:23], off nt
	s_nop 0
	v_addc_co_u32_e32 v85, vcc, 0, v83, vcc
	v_add_co_u32_e32 v86, vcc, s16, v82
	global_load_dwordx4 v[22:25], v[24:25], off nt
	s_nop 0
	global_load_dwordx4 v[26:29], v[50:51], off nt
	global_load_dwordx4 v[30:33], v[52:53], off nt
	global_load_dwordx4 v[34:37], v[54:55], off nt
	global_load_dwordx4 v[38:41], v[56:57], off nt
	global_load_dwordx4 v[42:45], v[58:59], off nt
	global_load_dwordx4 v[46:49], v[60:61], off nt
	v_addc_co_u32_e32 v87, vcc, 0, v83, vcc
	v_add_co_u32_e32 v88, vcc, s17, v82
	s_ashr_i32 s28, s24, 8
	s_nop 0
	v_addc_co_u32_e32 v89, vcc, 0, v83, vcc
	v_add_co_u32_e32 v90, vcc, s18, v82
	s_mulk_i32 s28, 0x58
	s_nop 0
	v_addc_co_u32_e32 v91, vcc, 0, v83, vcc
	v_add_co_u32_e32 v92, vcc, s19, v82
	s_ashr_i32 s29, s27, 31
	s_nop 0
	v_addc_co_u32_e32 v93, vcc, 0, v83, vcc
	v_add_co_u32_e32 v94, vcc, s20, v82
	s_ashr_i32 s23, s28, 31
	s_nop 0
	v_addc_co_u32_e32 v95, vcc, 0, v83, vcc
	v_add_co_u32_e32 v96, vcc, s21, v82
	s_add_u32 s24, s28, s27
	s_nop 0
	v_addc_co_u32_e32 v97, vcc, 0, v83, vcc
	global_load_dwordx4 v[50:53], v[82:83], off nt
	global_load_dwordx4 v[54:57], v[84:85], off nt
	global_load_dwordx4 v[58:61], v[86:87], off nt
	global_load_dwordx4 v[62:65], v[88:89], off nt
	global_load_dwordx4 v[66:69], v[90:91], off nt
	global_load_dwordx4 v[70:73], v[92:93], off nt
	global_load_dwordx4 v[74:77], v[94:95], off nt
	global_load_dwordx4 v[78:81], v[96:97], off nt
	s_addc_u32 s25, s23, s29
	s_lshl_b64 s[24:25], s[24:25], 15
	s_add_u32 s24, s6, s24
	v_add_u32_e32 v4, s9, v16
	s_addc_u32 s25, s7, s25
	s_ashr_i32 s22, s22, 8
	v_and_b32_e32 v4, 0x3f00, v4
	s_mulk_i32 s22, 0x58
	v_add_u32_e32 v17, 0x80, v17
	v_lshlrev_b32_e32 v4, 1, v4
	s_ashr_i32 s23, s26, 31
	s_ashr_i32 s27, s22, 31
	v_and_b32_e32 v17, 0x3f80, v17
	v_lshl_add_u64 v[82:83], s[24:25], 0, v[4:5]
	v_lshlrev_b32_e32 v4, 1, v99
	s_add_u32 s22, s22, s26
	v_lshl_add_u64 v[94:95], v[82:83], 0, v[8:9]
	v_lshl_add_u64 v[82:83], s[24:25], 0, v[4:5]
	v_lshlrev_b32_e32 v4, 1, v17
	s_addc_u32 s23, s27, s23
	v_lshl_add_u64 v[96:97], v[82:83], 0, v[8:9]
	v_lshl_add_u64 v[82:83], s[24:25], 0, v[4:5]
	v_lshlrev_b32_e32 v4, 1, v98
	s_lshl_b64 s[22:23], s[22:23], 15
	v_lshl_add_u64 v[98:99], v[82:83], 0, v[8:9]
	v_lshl_add_u64 v[82:83], s[24:25], 0, v[4:5]
	s_add_u32 s24, s6, s22
	v_and_b32_e32 v4, 0x7e00, v100
	s_addc_u32 s25, s7, s23
	v_lshl_add_u64 v[100:101], v[82:83], 0, v[8:9]
	v_lshl_add_u64 v[82:83], s[24:25], 0, v[4:5]
	v_and_b32_e32 v4, 0x7e80, v102
	v_lshl_add_u64 v[102:103], v[82:83], 0, v[8:9]
	v_lshl_add_u64 v[82:83], s[24:25], 0, v[4:5]
	v_and_b32_e32 v4, 0x7f00, v104
	s_add_i32 s0, s0, s8
	s_add_i32 s13, s13, s8
	v_lshl_add_u64 v[104:105], v[82:83], 0, v[8:9]
	v_lshl_add_u64 v[82:83], s[24:25], 0, v[4:5]
	v_and_b32_e32 v4, 0x7f80, v106
	s_add_i32 s9, s9, s10
	s_add_i32 s11, s11, s12
	s_add_i32 s22, s0, s1
	s_add_i32 s23, s14, s13
	v_lshl_add_u64 v[106:107], v[82:83], 0, v[8:9]
	v_lshl_add_u64 v[82:83], s[24:25], 0, v[4:5]
	s_cmpk_lt_i32 s23, 0x1600
	v_lshl_add_u64 v[108:109], v[82:83], 0, v[8:9]
	s_waitcnt vmcnt(0)
	v_cvt_pk_bf16_f32 v82, v18, v22
	v_cvt_pk_bf16_f32 v86, v19, v23
	v_cvt_pk_bf16_f32 v90, v20, v24
	v_cvt_pk_bf16_f32 v18, v21, v25
	v_cvt_pk_bf16_f32 v83, v26, v30
	v_cvt_pk_bf16_f32 v84, v34, v38
	v_cvt_pk_bf16_f32 v85, v42, v46
	v_cvt_pk_bf16_f32 v87, v27, v31
	v_cvt_pk_bf16_f32 v88, v35, v39
	v_cvt_pk_bf16_f32 v89, v43, v47
	v_cvt_pk_bf16_f32 v91, v28, v32
	v_cvt_pk_bf16_f32 v92, v36, v40
	v_cvt_pk_bf16_f32 v93, v44, v48
	v_cvt_pk_bf16_f32 v19, v29, v33
	v_cvt_pk_bf16_f32 v20, v37, v41
	v_cvt_pk_bf16_f32 v21, v45, v49
	v_cvt_pk_bf16_f32 v22, v50, v54
	v_cvt_pk_bf16_f32 v26, v51, v55
	v_cvt_pk_bf16_f32 v23, v58, v62
	v_cvt_pk_bf16_f32 v27, v59, v63
	v_cvt_pk_bf16_f32 v24, v66, v70
	v_cvt_pk_bf16_f32 v28, v67, v71
	v_cvt_pk_bf16_f32 v25, v74, v78
	v_cvt_pk_bf16_f32 v29, v75, v79
	v_cvt_pk_bf16_f32 v30, v52, v56
	v_cvt_pk_bf16_f32 v31, v60, v64
	v_cvt_pk_bf16_f32 v32, v68, v72
	v_cvt_pk_bf16_f32 v33, v76, v80
	v_cvt_pk_bf16_f32 v34, v53, v57
	v_cvt_pk_bf16_f32 v35, v61, v65
	v_cvt_pk_bf16_f32 v36, v69, v73
	v_cvt_pk_bf16_f32 v37, v77, v81
	global_store_dwordx4 v[94:95], v[22:25], off sc1
	global_store_dwordx4 v[96:97], v[26:29], off sc1
	global_store_dwordx4 v[98:99], v[30:33], off sc1
	global_store_dwordx4 v[100:101], v[34:37], off sc1
	global_store_dwordx4 v[102:103], v[82:85], off sc1
	global_store_dwordx4 v[104:105], v[86:89], off sc1
	global_store_dwordx4 v[106:107], v[90:93], off sc1
	global_store_dwordx4 v[108:109], v[18:21], off sc1
	s_cbranch_scc1 .LBB0_996
	s_add_i32 s0, s30, s13
.LBB0_998:
	s_cmpk_gt_i32 s0, 0x15ff
	s_cbranch_scc1 .Lmy_td10
	s_ashr_i32 s1, s0, 31
	s_lshr_b32 s1, s1, 26
	s_add_i32 s1, s0, s1
	s_ashr_i32 s8, s1, 6
	s_andn2_b32 s1, s1, 63
	v_and_b32_e32 v42, 56, v10
	v_or_b32_e32 v4, s1, v42
	s_lshl_b32 s6, s8, 11
	s_lshl_b32 s9, s0, 5
	v_ashrrev_i32_e32 v5, 31, v4
	s_sub_i32 s0, s9, s6
	v_lshlrev_b64 v[4:5], 13, v[4:5]
	v_lshl_add_u64 v[4:5], s[46:47], 0, v[4:5]
	s_ashr_i32 s1, s0, 31
	v_lshlrev_b32_e32 v1, 1, v1
	v_lshl_add_u64 v[4:5], s[0:1], 2, v[4:5]
	v_and_b32_e32 v36, 0x70, v1
	v_mov_b32_e32 v37, 0
	v_lshl_add_u64 v[28:29], v[4:5], 0, v[36:37]
	s_movk_i32 s1, 0x2000
	v_add_co_u32_e32 v12, vcc, s1, v28
	s_movk_i32 s1, 0x4000
	s_nop 0
	v_addc_co_u32_e32 v13, vcc, 0, v29, vcc
	v_add_co_u32_e32 v20, vcc, s1, v28
	s_movk_i32 s1, 0x6000
	s_nop 0
	v_addc_co_u32_e32 v21, vcc, 0, v29, vcc
	v_add_co_u32_e32 v22, vcc, s1, v28
	s_mov_b32 s1, 0x8000
	s_nop 0
	v_addc_co_u32_e32 v23, vcc, 0, v29, vcc
	v_add_co_u32_e32 v30, vcc, s1, v28
	s_mov_b32 s1, 0xa000
	s_nop 0
	v_addc_co_u32_e32 v31, vcc, 0, v29, vcc
	v_add_co_u32_e32 v32, vcc, s1, v28
	s_mov_b32 s1, 0xc000
	s_nop 0
	v_addc_co_u32_e32 v33, vcc, 0, v29, vcc
	v_add_co_u32_e32 v38, vcc, s1, v28
	s_mov_b32 s1, 0xe000
	s_nop 0
	v_addc_co_u32_e32 v39, vcc, 0, v29, vcc
	v_add_co_u32_e32 v40, vcc, s1, v28
	global_load_dwordx4 v[4:7], v[28:29], off nt
	global_load_dwordx4 v[8:11], v[12:13], off nt
	s_nop 0
	global_load_dwordx4 v[12:15], v[20:21], off nt
	global_load_dwordx4 v[16:19], v[22:23], off nt
	s_nop 0
	global_load_dwordx4 v[20:23], v[30:31], off nt
	global_load_dwordx4 v[24:27], v[32:33], off nt
	v_addc_co_u32_e32 v41, vcc, 0, v29, vcc
	global_load_dwordx4 v[28:31], v[38:39], off nt
	global_load_dwordx4 v[32:35], v[40:41], off nt
	s_ashr_i32 s0, s0, 8
	s_mulk_i32 s0, 0x58
	v_or_b32_e32 v1, s9, v3
	s_ashr_i32 s1, s8, 31
	s_ashr_i32 s9, s0, 31
	s_add_u32 s0, s0, s8
	s_addc_u32 s1, s9, s1
	s_lshl_b64 s[0:1], s[0:1], 15
	v_lshlrev_b32_e32 v1, 7, v1
	s_add_u32 s0, s50, s0
	v_and_b32_e32 v36, 0x7e00, v1
	s_addc_u32 s1, s51, s1
	v_lshl_add_u64 v[2:3], s[0:1], 0, v[36:37]
	v_lshlrev_b32_e32 v36, 1, v42
	s_mov_b32 s10, 0x9600000
	v_lshl_add_u64 v[2:3], v[2:3], 0, v[36:37]
	s_mov_b64 s[6:7], 0x9600000
	v_add_co_u32_e32 v42, vcc, s10, v2
	v_lshl_add_u64 v[40:41], v[2:3], 0, s[6:7]
	s_nop 0
	v_addc_co_u32_e32 v43, vcc, 0, v3, vcc
	s_waitcnt vmcnt(0)
	v_cvt_pk_bf16_f32 v36, v4, v8
	v_cvt_pk_bf16_f32 v2, v5, v9
	v_cvt_pk_bf16_f32 v3, v13, v17
	v_cvt_pk_bf16_f32 v4, v21, v25
	v_cvt_pk_bf16_f32 v37, v12, v16
	v_cvt_pk_bf16_f32 v5, v29, v33
	global_store_dwordx4 v[40:41], v[2:5], off offset:128 sc1
	v_cvt_pk_bf16_f32 v38, v20, v24
	v_cvt_pk_bf16_f32 v39, v28, v32
	v_cvt_pk_bf16_f32 v2, v6, v10
	v_cvt_pk_bf16_f32 v3, v14, v18
	v_cvt_pk_bf16_f32 v4, v22, v26
	v_cvt_pk_bf16_f32 v5, v30, v34
	global_store_dwordx4 v[40:41], v[2:5], off offset:256 sc1
	global_store_dwordx4 v[42:43], v[36:39], off sc1
	s_nop 0
	v_cvt_pk_bf16_f32 v2, v7, v11
	v_cvt_pk_bf16_f32 v3, v15, v19
	v_cvt_pk_bf16_f32 v4, v23, v27
	v_cvt_pk_bf16_f32 v5, v31, v35
	global_store_dwordx4 v[40:41], v[2:5], off offset:384 sc1
.Lmy_td10:
	s_waitcnt vmcnt(0)
	s_mov_b64 s[6:7], exec
	s_mov_b64 exec, 1
	v_mov_b32_e32 v2, 0x34840
	v_mov_b32_e32 v3, 1
	global_atomic_add v2, v3, s[50:51]
	s_mov_b64 exec, s[6:7]
.LBB0_1000:
	v_readlane_b32 s0, v254, 0
	v_readlane_b32 s1, v254, 1
	s_cmp_gt_i32 s1, 11
	s_cselect_b64 s[0:1], -1, 0
	s_and_b64 s[4:5], s[4:5], s[0:1]
	s_andn2_b64 vcc, exec, s[4:5]
	s_cbranch_vccnz .LBB0_1054
	s_waitcnt vmcnt(0)
	s_waitcnt vmcnt(0)
	s_barrier
	s_mov_b64 s[4:5], exec
	v_readlane_b32 s6, v254, 7
	v_readlane_b32 s7, v254, 8
	s_and_b64 s[6:7], s[4:5], s[6:7]
	s_mov_b64 exec, s[6:7]
	s_cbranch_execz .LBB0_1053
	s_cmpk_lg_i32 s3, 0x100
	s_cbranch_scc1 .Lmy_gb10_orig
	s_and_b32 s6, s2, 7
	s_lshl_b32 s6, s6, 6
	s_add_u32 s6, s6, 0x34800
	v_mov_b32_e32 v2, s6
	v_mov_b32_e32 v3, 1
	global_atomic_add v2, v3, s[50:51]
	s_movk_i32 s7, 0x4000

.Lmy_gb10_go:
	v_mov_b32_e32 v2, 0x34840
	s_movk_i32 s7, 0x4000

.Lmy_gb10_orig:
	s_add_i32 s6, 0, 0x23fc0
	v_mov_b32_e32 v1, s6
	s_waitcnt vmcnt(0) expcnt(0) lgkmcnt(0)
	ds_read_b32 v3, v1
	s_add_i32 s6, 0, 0x23fc4
	v_mov_b32_e32 v1, s6
	ds_read_b32 v1, v1
	s_waitcnt lgkmcnt(1)
	v_cmp_ne_u32_e32 vcc, 0, v3
	s_cbranch_vccnz .LBB0_1017
	v_readlane_b32 s6, v254, 2
	v_readlane_b32 s7, v254, 3
	s_load_dwordx2 s[10:11], s[6:7], 0x4
	s_add_u32 s6, s50, 0x28200
	s_addc_u32 s7, s51, 0
	s_add_u32 s8, s50, 0x28400
	s_addc_u32 s9, s51, 0
	s_waitcnt lgkmcnt(0)
	s_mul_i32 s30, s10, s3
	s_add_u32 s10, s50, 0x28500
	s_mul_i32 s30, s30, s11
	s_addc_u32 s11, s51, 0
	s_add_u32 s12, s50, 0x28600
	s_addc_u32 s13, s51, 0
	s_add_u32 s14, s50, 0x28700
	s_addc_u32 s15, s51, 0
	s_add_u32 s16, s50, 0x28800
	s_addc_u32 s17, s51, 0
	s_add_u32 s18, s50, 0x28900
	s_addc_u32 s19, s51, 0
	s_add_u32 s20, s50, 0x28a00
	s_addc_u32 s21, s51, 0
	s_add_u32 s22, s50, 0x28b00
	s_addc_u32 s23, s51, 0
	s_add_u32 s24, s50, 0x28c00
	s_addc_u32 s25, s51, 0
	s_add_u32 s26, s50, 0x28d00
	s_addc_u32 s27, s51, 0
	s_add_u32 s28, s50, 0x28e00
	s_addc_u32 s29, s51, 0
	s_add_u32 s36, s50, 0x28f00
	s_addc_u32 s37, s51, 0
	s_add_u32 s40, s50, 0x29000
	s_addc_u32 s41, s51, 0
	s_add_u32 s42, s50, 0x29100
	s_addc_u32 s43, s51, 0
	s_add_u32 s44, s50, 0x29200
	s_addc_u32 s45, s51, 0
	s_add_u32 s46, s50, 0x29300
	s_addc_u32 s47, s51, 0
	s_mov_b32 s31, 1
	v_mov_b32_e32 v17, 0
	s_branch .LBB0_1005
